# one L1 invalidate per CU per barrier: last arriver on the CU (HW_ID key, spare barrier words) invalidates; pairing used only when exactly two workgroups registered on the CU
# baseline (speedup 1.0000x reference)
; __device__ __forceinline__ unsigned xb_ld(unsigned* p)              { return __hip_atomic_load(p, __ATOMIC_RELAXED, __HIP_MEMORY_SCOPE_AGENT); }
; __device__ __forceinline__ void xcd_barrier_complete(unsigned* bar, unsigned x, unsigned& nloc, unsigned& nx) {
;     ...
;     for (unsigned j = 0; j < 16; ++j) { const unsigned c = xb_ld(&bar[XB_XCNT(j)]); sum += c; cnt += (c > 0u) ? 1u : 0u; mine = (j == x) ? c : mine; }
;     if (sum == G) break;
;     __builtin_amdgcn_s_sleep(1);
;     if ((++sp & 255u) == 0u) { if (xb_ld(&bar[XB_TMO])) break; if (sp > XB_SPIN_CAP) { atomicAdd(&bar[XB_TMO], 1u); break; } }
;   }
;   nloc = mine > 0u ? mine : 1u; nx = cnt > 0u ? cnt : 1u;
; }
; __device__ __forceinline__ void xcd_barrier(const XcdBarrier& b) {
;   asm volatile("s_waitcnt vmcnt(0)" ::: "memory");
;   __syncthreads();
;   if (threadIdx.x == 0) {
;     unsigned* bar = b.bar;
;     __builtin_amdgcn_s_waitcnt(0);
;     unsigned nloc = b.st[0], nx = b.st[1];
;     if (nloc == 0u) { xcd_barrier_complete(bar, b.x, nloc, nx); b.st[0] = nloc; b.st[1] = nx; }
.LBB0_31:
	v_readlane_b32 s4, v229, 26
	s_cmp_eq_u32 s4, 0
	s_cselect_b64 vcc, -1, 0
	s_cmp_eq_u32 s4, 1
	v_cndmask_b32_e32 v16, 0, v11, vcc
	s_cselect_b64 vcc, -1, 0
	s_cmp_eq_u32 s4, 2
	v_cndmask_b32_e32 v16, v16, v0, vcc
	s_cselect_b64 vcc, -1, 0
	s_cmp_eq_u32 s4, 3
	v_cndmask_b32_e32 v16, v16, v1, vcc
	s_cselect_b64 vcc, -1, 0
	s_cmp_eq_u32 s4, 4
	v_cndmask_b32_e32 v16, v16, v2, vcc
	s_cselect_b64 vcc, -1, 0
	s_cmp_eq_u32 s4, 5
	v_cndmask_b32_e32 v16, v16, v3, vcc
	s_cselect_b64 vcc, -1, 0
	s_cmp_eq_u32 s4, 6
	v_cndmask_b32_e32 v16, v16, v4, vcc
	s_cselect_b64 vcc, -1, 0
	s_cmp_eq_u32 s4, 7
	v_cndmask_b32_e32 v16, v16, v5, vcc
	s_cselect_b64 vcc, -1, 0
	s_cmp_eq_u32 s4, 8
	v_cndmask_b32_e32 v16, v16, v6, vcc
	s_cselect_b64 vcc, -1, 0
	s_cmp_eq_u32 s4, 9
	v_cndmask_b32_e32 v16, v16, v7, vcc
	s_cselect_b64 vcc, -1, 0
	s_cmp_eq_u32 s4, 10
	v_cndmask_b32_e32 v16, v16, v8, vcc
	s_cselect_b64 vcc, -1, 0
	s_cmp_eq_u32 s4, 11
	v_cndmask_b32_e32 v16, v16, v9, vcc
	s_cselect_b64 vcc, -1, 0
	s_cmp_eq_u32 s4, 12
	v_cndmask_b32_e32 v16, v16, v10, vcc
	s_cselect_b64 vcc, -1, 0
	s_cmp_eq_u32 s4, 13
	v_cndmask_b32_e32 v16, v16, v12, vcc
	s_cselect_b64 vcc, -1, 0
	s_cmp_eq_u32 s4, 14
	v_cndmask_b32_e32 v16, v16, v13, vcc
	s_cselect_b64 vcc, -1, 0
	s_cmp_eq_u32 s4, 15
	v_cndmask_b32_e32 v16, v16, v14, vcc
	s_cselect_b64 vcc, -1, 0
	v_cndmask_b32_e32 v16, v16, v15, vcc
	v_cmp_ne_u32_e32 vcc, 0, v11
	s_nop 1
	v_cndmask_b32_e64 v11, 0, 1, vcc
	v_cmp_ne_u32_e32 vcc, 0, v0
	s_nop 1
	v_addc_co_u32_e32 v0, vcc, 0, v11, vcc
	v_cmp_ne_u32_e32 vcc, 0, v1
	s_nop 1
	v_cndmask_b32_e64 v1, 0, 1, vcc
	v_cmp_ne_u32_e32 vcc, 0, v2
	v_max_u32_e32 v2, 1, v16
	s_nop 0
	v_addc_co_u32_e32 v0, vcc, v0, v1, vcc
	v_cmp_ne_u32_e32 vcc, 0, v3
	s_nop 1
	v_cndmask_b32_e64 v1, 0, 1, vcc
	v_cmp_ne_u32_e32 vcc, 0, v4
	s_nop 1
	v_addc_co_u32_e32 v0, vcc, v0, v1, vcc
	v_cmp_ne_u32_e32 vcc, 0, v5
	s_nop 1
	v_cndmask_b32_e64 v1, 0, 1, vcc
	v_cmp_ne_u32_e32 vcc, 0, v6
	s_nop 1
	v_addc_co_u32_e32 v0, vcc, v0, v1, vcc
	v_cmp_ne_u32_e32 vcc, 0, v7
	s_nop 1
	v_cndmask_b32_e64 v1, 0, 1, vcc
	v_cmp_ne_u32_e32 vcc, 0, v8
	s_nop 1
	v_addc_co_u32_e32 v0, vcc, v0, v1, vcc
	v_cmp_ne_u32_e32 vcc, 0, v9
	s_nop 1
	v_cndmask_b32_e64 v1, 0, 1, vcc
	v_cmp_ne_u32_e32 vcc, 0, v10
	s_nop 1
	v_addc_co_u32_e32 v0, vcc, v0, v1, vcc
	v_cmp_ne_u32_e32 vcc, 0, v12
	s_nop 1
	v_cndmask_b32_e64 v1, 0, 1, vcc
	v_cmp_ne_u32_e32 vcc, 0, v13
	s_nop 1
	v_addc_co_u32_e32 v0, vcc, v0, v1, vcc
	v_cmp_ne_u32_e32 vcc, 0, v14
	s_nop 1
	v_cndmask_b32_e64 v1, 0, 1, vcc
	v_cmp_ne_u32_e32 vcc, 0, v15
	s_nop 1
	v_addc_co_u32_e32 v0, vcc, v0, v1, vcc
	v_max_u32_e32 v0, 1, v0
	ds_write_b32 v133, v2
	ds_write_b32 v137, v0
	v_readlane_b32 s12, v229, 58
	s_nop 3
	s_cmp_eq_u32 s12, 0
	s_cbranch_scc1 .Lxb_ncu0
	v_mov_b32_e32 v8, s12
	global_load_dword v8, v8, s[34:35] sc1
	s_waitcnt vmcnt(0)
	v_readfirstlane_b32 s13, v8
	s_nop 3
	s_lshr_b32 s13, s13, 16
	s_cmp_eq_u32 s13, 2
	s_cselect_b32 s12, s12, 0
	s_cselect_b32 s13, s13, 0
	s_sub_u32 s14, s13, 1
	s_cmp_eq_u32 s13, 0
	s_cselect_b32 s14, 0, s14
	s_nop 0
	v_writelane_b32 v229, s12, 58
	v_writelane_b32 v229, s13, 59
	v_writelane_b32 v229, s14, 60

; #define LAS __attribute__((address_space(3)))
; __device__ __forceinline__ unsigned xb_add(unsigned* p, unsigned v) { return __hip_atomic_fetch_add(p, v, __ATOMIC_RELAXED, __HIP_MEMORY_SCOPE_AGENT); }
; __device__ __forceinline__ unsigned xb_xcc_id() { return (unsigned)__builtin_amdgcn_s_getreg((3 << 11) | 20) & 0xFu; }
; __device__ __forceinline__ XcdBarrier xcd_barrier_post(unsigned* bar, volatile LAS unsigned* st) {
;   XcdBarrier b; b.bar = bar; b.x = xb_xcc_id(); b.st = st;
;   if (threadIdx.x == 0) (void)xb_add(&bar[XB_XCNT(b.x)], 1u);
;   return b;
; }
.LBB0_76:
	s_or_b64 exec, exec, s[6:7]
	s_barrier
	s_getreg_b32 s4, hwreg(HW_REG_XCC_ID, 0, 4)
	s_and_b32 s4, s4, 15
	v_writelane_b32 v229, s4, 26
	s_mov_b64 s[6:7], exec
	v_readlane_b32 s8, v230, 3
	v_readlane_b32 s9, v230, 4
	s_and_b64 s[8:9], s[6:7], s[8:9]
	s_mov_b64 exec, s[8:9]
	s_cbranch_execz .LBB0_79
	s_mov_b64 s[8:9], exec
	v_mbcnt_lo_u32_b32 v0, s8, 0
	v_mbcnt_hi_u32_b32 v0, s9, v0
	v_cmp_eq_u32_e32 vcc, 0, v0
	s_and_b64 s[10:11], exec, vcc
	s_mov_b64 exec, s[10:11]
	s_cbranch_execz .LBB0_79
	s_getreg_b32 s10, hwreg(HW_REG_HW_ID)
	v_readlane_b32 s4, v229, 26
	s_lshr_b32 s10, s10, 8
	s_and_b32 s11, s10, 0xff
	s_and_b32 s12, s11, 0x90
	s_and_b32 s13, s11, 15
	s_lshr_b32 s14, s11, 5
	s_and_b32 s14, s14, 3
	s_lshl_b32 s14, s14, 4
	s_or_b32 s13, s13, s14
	s_cmp_eq_u32 s12, 0
	s_cselect_b32 s15, 1, 0
	s_cmp_lg_u32 s13, 0
	s_cselect_b32 s14, 1, 0
	s_and_b32 s15, s15, s14
	s_cmp_lt_u32 s4, 8
	s_cselect_b32 s14, 1, 0
	s_and_b32 s15, s15, s14
	s_add_u32 s14, s4, 8
	s_lshl_b32 s14, s14, 6
	s_add_u32 s14, s14, 0x900
	s_add_u32 s14, s14, s13
	s_lshl_b32 s14, s14, 2
	s_cmp_lg_u32 s15, 0
	s_cselect_b32 s14, s14, 0
	s_nop 0
	v_writelane_b32 v229, s14, 58
	s_cbranch_scc0 .Lxb_noreg
	v_mov_b32_e32 v2, s14
	v_mov_b32_e32 v4, 0x10000
	global_atomic_add v3, v2, v4, s[34:35] sc0
	s_waitcnt vmcnt(0)
